# GLA sequential pass touches the cache lines of the chunks two steps ahead (same acquired group) so its chunk loads hit L2
# baseline (speedup 1.0000x reference)
.LBB0_670:
	v_mov_b64_e32 v[54:55], v[22:23]
	v_mov_b64_e32 v[52:53], v[20:21]
	s_waitcnt vmcnt(4)
	s_and_b32 s88, s18, 6
	s_cmp_eq_u32 s88, 6
	s_cbranch_scc1 .Lst_skip_b
	s_cmp_gt_u32 s35, 58
	s_cbranch_scc1 .Lst_skip_b
	s_add_i32 s93, s35, 5
	s_add_u32 s90, s14, s93
	s_addc_u32 s91, s15, 0
	s_lshl_b32 s94, s93, 6
	s_add_u32 s94, s94, s10
	s_addc_u32 s95, s11, 0
	s_lshl_b64 s[96:97], s[90:91], 14
	s_add_u32 s96, s3, s96
	s_addc_u32 s97, s30, s97
	v_lshl_add_u64 v[224:225], s[96:97], 0, v[98:99]
	v_lshl_add_u64 v[226:227], v[224:225], 0, v[100:101]
	global_load_dword v240, v[226:227], off
	v_lshl_add_u64 v[226:227], s[96:97], 0, v[102:103]
	v_lshl_add_u64 v[226:227], v[226:227], 0, v[100:101]
	global_load_dword v240, v[226:227], off
	v_mov_b32_e32 v229, s95
	v_or_b32_e32 v228, s94, v97
	v_lshlrev_b64 v[228:229], 10, v[228:229]
	v_lshl_add_u64 v[228:229], v[108:109], 0, v[228:229]
	global_load_dword v240, v[228:229], off
	v_lshl_add_u64 v[228:229], s[94:95], 0, v[104:105]
	v_lshlrev_b64 v[228:229], 10, v[228:229]
	v_lshl_add_u64 v[228:229], v[108:109], 0, v[228:229]
	global_load_dword v240, v[228:229], off
	s_lshl_b64 s[96:97], s[90:91], 15
	v_lshl_or_b32 v230, v112, 7, s96
	v_mov_b32_e32 v231, s97
	v_lshl_add_u64 v[230:231], v[118:119], 0, v[230:231]
	global_load_dword v240, v[230:231], off
	global_load_dword v240, v[230:231], off offset:64
.Lst_skip_b:
	v_mov_b64_e32 v[16:17], v[92:93]
	v_mov_b64_e32 v[20:21], v[88:89]
	s_andn2_b64 vcc, exec, s[22:23]
	s_mov_b32 s35, s18
	v_mov_b64_e32 v[18:19], v[94:95]
	v_mov_b64_e32 v[22:23], v[90:91]
	s_waitcnt lgkmcnt(0)
	s_barrier
	s_cbranch_vccz .LBB0_699

.LBB0_690:
	v_add_u32_e32 v111, 0x4800, v129
	v_cvt_pk_bf16_f32 v88, v84, v85
	v_cvt_pk_bf16_f32 v89, v86, v87
	v_cvt_pk_bf16_f32 v90, v80, v81
	v_cvt_pk_bf16_f32 v91, v82, v83
	ds_read2_b64 v[144:147], v111 offset1:4
	v_cvt_pk_bf16_f32 v92, v76, v77
	v_cvt_pk_bf16_f32 v93, v78, v79
	v_cvt_pk_bf16_f32 v94, v72, v73
	v_cvt_pk_bf16_f32 v95, v74, v75
	ds_read2_b64 v[152:155], v111 offset0:8 offset1:12
	s_waitcnt lgkmcnt(1)
	v_mfma_f32_16x16x32_bf16 v[144:147], v[88:91], v[144:147], 0
	v_cvt_pk_bf16_f32 v148, v68, v69
	v_cvt_pk_bf16_f32 v149, v70, v71
	v_cvt_pk_bf16_f32 v150, v64, v65
	v_cvt_pk_bf16_f32 v151, v66, v67
	ds_read2_b64 v[162:165], v111 offset0:16 offset1:20
	s_waitcnt lgkmcnt(1)
	v_mfma_f32_16x16x32_bf16 v[144:147], v[92:95], v[152:155], v[144:147]
	v_cvt_pk_bf16_f32 v158, v60, v61
	v_cvt_pk_bf16_f32 v159, v62, v63
	v_cvt_pk_bf16_f32 v160, v56, v57
	v_cvt_pk_bf16_f32 v161, v58, v59
	ds_read2_b64 v[152:155], v111 offset0:24 offset1:28
	s_waitcnt lgkmcnt(1)
	v_mfma_f32_16x16x32_bf16 v[144:147], v[148:151], v[162:165], v[144:147]
	v_add_u32_e32 v111, 0x5800, v129
	ds_read2_b64 v[162:165], v111 offset0:40 offset1:44
	v_lshl_or_b32 v123, s35, 6, v124
	s_waitcnt lgkmcnt(1)
	v_mfma_f32_16x16x32_bf16 v[144:147], v[158:161], v[152:155], v[144:147]
	ds_read2_b64 v[152:155], v111 offset0:32 offset1:36
	v_or_b32_e32 v174, s10, v123
	v_mov_b32_e32 v175, s11
	s_waitcnt lgkmcnt(0)
	v_mfma_f32_16x16x32_bf16 v[152:155], v[88:91], v[152:155], 0
	v_add_u32_e32 v143, 0, v106
	v_lshlrev_b64 v[178:179], 12, v[174:175]
	v_lshl_add_u64 v[180:181], v[116:117], 0, v[178:179]
	v_mfma_f32_16x16x32_bf16 v[152:155], v[92:95], v[162:165], v[152:155]
	ds_read2_b64 v[162:165], v111 offset0:48 offset1:52
	s_lshl_b32 s24, s12, 2
	s_mov_b32 s25, s19
	s_waitcnt lgkmcnt(0)
	v_mfma_f32_16x16x32_bf16 v[152:155], v[148:151], v[162:165], v[152:155]
	ds_read2_b64 v[162:165], v111 offset0:56 offset1:60
	v_add_u32_e32 v111, 0x6800, v129
	ds_read2_b64 v[166:169], v111 offset0:72 offset1:76
	s_waitcnt lgkmcnt(1)
	v_mfma_f32_16x16x32_bf16 v[152:155], v[158:161], v[162:165], v[152:155]
	ds_read2_b64 v[162:165], v111 offset0:64 offset1:68
	ds_read2_b64 v[170:173], v111 offset0:88 offset1:92
	v_mov_b32_e32 v123, v101
	s_waitcnt lgkmcnt(1)
	v_mfma_f32_16x16x32_bf16 v[162:165], v[88:91], v[162:165], 0
	v_mfma_f32_16x16x32_bf16 v[162:165], v[92:95], v[166:169], v[162:165]
	ds_read2_b64 v[166:169], v111 offset0:80 offset1:84
	v_add_u32_e32 v111, 0x7800, v129
	s_waitcnt lgkmcnt(0)
	v_mfma_f32_16x16x32_bf16 v[162:165], v[148:151], v[166:169], v[162:165]
	ds_read2_b64 v[166:169], v111 offset0:96 offset1:100
	v_mfma_f32_16x16x32_bf16 v[162:165], v[158:161], v[170:173], v[162:165]
	ds_read2_b64 v[170:173], v111 offset0:104 offset1:108
	s_waitcnt lgkmcnt(1)
	v_mfma_f32_16x16x32_bf16 v[88:91], v[88:91], v[166:169], 0
	ds_read2_b64 v[166:169], v111 offset0:112 offset1:116
	ds_read2_b64 v[174:177], v111 offset0:120 offset1:124
	v_mov_b32_e32 v111, v101
	s_waitcnt lgkmcnt(2)
	v_mfma_f32_16x16x32_bf16 v[88:91], v[92:95], v[170:173], v[88:91]
	ds_read_b128 v[92:95], v143 offset:35840
	ds_read_b128 v[170:173], v133
	global_store_dwordx4 v[180:181], v[144:147], off
	s_waitcnt lgkmcnt(1)
	v_pk_mul_f32 v[84:85], v[84:85], v[92:93]
	v_mfma_f32_16x16x32_bf16 v[88:91], v[148:151], v[166:169], v[88:91]
	ds_read_b128 v[144:147], v133 offset:64
	ds_read_b128 v[148:151], v143 offset:35904
	v_pk_mul_f32 v[86:87], v[86:87], v[94:95]
	ds_read_b128 v[92:95], v133 offset:2304
	v_mfma_f32_16x16x32_bf16 v[88:91], v[158:161], v[174:177], v[88:91]
	ds_read_b128 v[158:161], v133 offset:2368
	s_waitcnt lgkmcnt(2)
	v_pk_mul_f32 v[80:81], v[80:81], v[148:149]
	v_pk_mul_f32 v[82:83], v[82:83], v[150:151]
	v_mfma_f32_16x16x32_bf16 v[84:87], v[170:173], v[52:55], v[84:87]
	v_lshl_add_u64 v[170:171], s[16:17], 0, v[178:179]
	v_mfma_f32_16x16x32_bf16 v[84:87], v[144:147], v[48:51], v[84:87]
	ds_read_b128 v[144:147], v143 offset:35968
	ds_read_b128 v[148:151], v133 offset:4608
	s_waitcnt lgkmcnt(1)
	v_pk_mul_f32 v[76:77], v[76:77], v[144:145]
	v_mfma_f32_16x16x32_bf16 v[80:83], v[92:95], v[52:55], v[80:83]
	ds_read_b128 v[92:95], v133 offset:4672
	ds_read_b128 v[166:169], v143 offset:36032
	v_pk_mul_f32 v[78:79], v[78:79], v[146:147]
	ds_read_b128 v[144:147], v133 offset:6912
	v_mfma_f32_16x16x32_bf16 v[80:83], v[158:161], v[48:51], v[80:83]
	ds_read_b128 v[158:161], v133 offset:9280
	s_waitcnt lgkmcnt(2)
	v_pk_mul_f32 v[72:73], v[72:73], v[166:167]
	v_pk_mul_f32 v[74:75], v[74:75], v[168:169]
	v_mfma_f32_16x16x32_bf16 v[76:79], v[148:151], v[52:55], v[76:79]
	ds_read_b128 v[148:151], v133 offset:6976
	s_waitcnt lgkmcnt(2)
	v_mfma_f32_16x16x32_bf16 v[72:75], v[144:147], v[52:55], v[72:75]
	ds_read_b128 v[144:147], v143 offset:36096
	v_mfma_f32_16x16x32_bf16 v[76:79], v[92:95], v[48:51], v[76:79]
	ds_read_b128 v[92:95], v133 offset:9216
	s_waitcnt lgkmcnt(2)
	v_mfma_f32_16x16x32_bf16 v[72:75], v[148:151], v[48:51], v[72:75]
	ds_read_b128 v[148:151], v143 offset:36160
	s_waitcnt lgkmcnt(2)
	v_pk_mul_f32 v[68:69], v[68:69], v[144:145]
	v_pk_mul_f32 v[70:71], v[70:71], v[146:147]
	ds_read_b128 v[144:147], v133 offset:11520
	s_waitcnt lgkmcnt(1)
	v_pk_mul_f32 v[64:65], v[64:65], v[148:149]
	v_mfma_f32_16x16x32_bf16 v[68:71], v[92:95], v[52:55], v[68:71]
	v_lshl_add_u64 v[92:93], v[170:171], 0, s[24:25]
	v_lshl_add_u64 v[92:93], v[92:93], 0, v[110:111]
	v_lshl_add_u64 v[166:167], v[92:93], 0, v[122:123]
	ds_read_b128 v[92:95], v133 offset:11584
	v_pk_mul_f32 v[66:67], v[66:67], v[150:151]
	v_mfma_f32_16x16x32_bf16 v[68:71], v[158:161], v[48:51], v[68:71]
	v_add_co_u32_e32 v158, vcc, s31, v166
	s_waitcnt lgkmcnt(1)
	v_mfma_f32_16x16x32_bf16 v[64:67], v[144:147], v[52:55], v[64:67]
	ds_read_b128 v[144:147], v143 offset:36224
	ds_read_b128 v[148:151], v133 offset:13824
	v_addc_co_u32_e32 v159, vcc, 0, v167, vcc
	global_store_dwordx4 v[158:159], v[152:155], off
	s_waitcnt lgkmcnt(1)
	v_pk_mul_f32 v[60:61], v[60:61], v[144:145]
	ds_read_b128 v[152:155], v133 offset:13888
	v_pk_mul_f32 v[62:63], v[62:63], v[146:147]
	ds_read_b128 v[144:147], v133 offset:16128
	v_mfma_f32_16x16x32_bf16 v[64:67], v[92:95], v[48:51], v[64:67]
	ds_read_b128 v[92:95], v143 offset:36288
	s_waitcnt lgkmcnt(3)
	v_mfma_f32_16x16x32_bf16 v[60:63], v[148:151], v[52:55], v[60:63]
	v_add_co_u32_e32 v148, vcc, s33, v166
	s_nop 1
	v_addc_co_u32_e32 v149, vcc, 0, v167, vcc
	global_store_dwordx4 v[148:149], v[162:165], off
	ds_read_b128 v[148:151], v133 offset:16192
	s_waitcnt lgkmcnt(1)
	v_pk_mul_f32 v[56:57], v[56:57], v[92:93]
	v_pk_mul_f32 v[58:59], v[58:59], v[94:95]
	v_mfma_f32_16x16x32_bf16 v[60:63], v[152:155], v[48:51], v[60:63]
	s_nop 0
	v_mfma_f32_16x16x32_bf16 v[52:55], v[144:147], v[52:55], v[56:59]
	s_waitcnt lgkmcnt(0)
	v_mfma_f32_16x16x32_bf16 v[48:51], v[148:151], v[48:51], v[52:55]
	s_nop 0
	v_add_co_u32_e32 v56, vcc, s34, v166
	s_nop 1
	v_addc_co_u32_e32 v57, vcc, 0, v167, vcc
	global_store_dwordx4 v[56:57], v[88:91], off
	ds_write_b128 v125, v[0:3] offset:36352
	ds_write_b128 v126, v[4:7] offset:54784
	ds_write_b128 v127, v[8:11] offset:36352
	ds_write_b128 v128, v[12:15] offset:54784
	s_and_saveexec_b64 s[26:27], s[4:5]
	ds_write_b32 v107, v130
	s_or_b64 exec, exec, s[26:27]
	s_waitcnt vmcnt(4)
	s_and_b32 s88, s18, 6
	s_cmp_eq_u32 s88, 6
	s_cbranch_scc1 .Lst_skip_a
	s_cmp_gt_u32 s35, 58
	s_cbranch_scc1 .Lst_skip_a
	s_add_i32 s93, s35, 4
	s_add_u32 s90, s14, s93
	s_addc_u32 s91, s15, 0
	s_lshl_b32 s94, s93, 6
	s_add_u32 s94, s94, s10
	s_addc_u32 s95, s11, 0
	s_lshl_b64 s[96:97], s[90:91], 14
	s_add_u32 s96, s3, s96
	s_addc_u32 s97, s30, s97
	v_lshl_add_u64 v[224:225], s[96:97], 0, v[98:99]
	v_lshl_add_u64 v[226:227], v[224:225], 0, v[100:101]
	global_load_dword v240, v[226:227], off
	v_lshl_add_u64 v[226:227], s[96:97], 0, v[102:103]
	v_lshl_add_u64 v[226:227], v[226:227], 0, v[100:101]
	global_load_dword v240, v[226:227], off
	v_mov_b32_e32 v229, s95
	v_or_b32_e32 v228, s94, v97
	v_lshlrev_b64 v[228:229], 10, v[228:229]
	v_lshl_add_u64 v[228:229], v[108:109], 0, v[228:229]
	global_load_dword v240, v[228:229], off
	v_lshl_add_u64 v[228:229], s[94:95], 0, v[104:105]
	v_lshlrev_b64 v[228:229], 10, v[228:229]
	v_lshl_add_u64 v[228:229], v[108:109], 0, v[228:229]
	global_load_dword v240, v[228:229], off
	s_lshl_b64 s[96:97], s[90:91], 15
	v_lshl_or_b32 v230, v112, 7, s96
	v_mov_b32_e32 v231, s97
	v_lshl_add_u64 v[230:231], v[118:119], 0, v[230:231]
	global_load_dword v240, v[230:231], off
	global_load_dword v240, v[230:231], off offset:64
.Lst_skip_a:
	v_mov_b64_e32 v[94:95], v[18:19]
	v_mov_b64_e32 v[90:91], v[22:23]
	s_and_b64 vcc, exec, s[6:7]
	v_mov_b64_e32 v[92:93], v[16:17]
	v_mov_b64_e32 v[88:89], v[20:21]
	s_waitcnt lgkmcnt(0)
	s_barrier
	s_cbranch_vccnz .LBB0_696
	s_add_i32 s26, s35, 3
	s_mov_b32 s27, s19
	s_add_u32 s6, s14, s26
	s_addc_u32 s7, s15, 0
	s_lshl_b64 s[26:27], s[26:27], 6
	s_add_u32 s26, s26, s10
	s_addc_u32 s27, s27, s11
	s_lshl_b64 s[28:29], s[6:7], 14
	s_add_u32 s28, s3, s28
	s_addc_u32 s29, s30, s29
	v_lshl_add_u64 v[0:1], s[28:29], 0, v[98:99]
	v_lshl_add_u64 v[8:9], v[0:1], 0, v[100:101]
	v_mov_b32_e32 v1, s27
	v_or_b32_e32 v0, s26, v97
	v_lshlrev_b64 v[0:1], 10, v[0:1]
	v_lshl_add_u64 v[10:11], v[108:109], 0, v[0:1]
	global_load_dwordx4 v[0:3], v[8:9], off
	global_load_dwordx4 v[4:7], v[10:11], off
	v_lshl_add_u64 v[10:11], s[26:27], 0, v[104:105]
	v_lshl_add_u64 v[8:9], s[28:29], 0, v[102:103]
	v_lshlrev_b64 v[10:11], 10, v[10:11]
	v_lshl_add_u64 v[8:9], v[8:9], 0, v[100:101]
	v_lshl_add_u64 v[12:13], v[108:109], 0, v[10:11]
	global_load_dwordx4 v[8:11], v[8:9], off
	s_nop 0
	global_load_dwordx4 v[12:15], v[12:13], off
	v_mov_b32_e32 v130, 0
	s_and_saveexec_b64 s[26:27], s[4:5]
	s_cbranch_execz .LBB0_695
	s_lshl_b64 s[28:29], s[6:7], 9
	v_lshl_add_u64 v[52:53], v[114:115], 0, s[28:29]
	global_load_dword v130, v[52:53], off
